# asm guide 7.3 also on the diff attention unit epilogue: v_permlane32_swap pairs + 8 dwordx4 stores instead of 16 dwordx2
# baseline (speedup 1.0000x reference)
.LBB0_611:
	s_andn2_b64 vcc, exec, s[18:19]
	s_waitcnt lgkmcnt(0)
	s_barrier
	s_cbranch_vccnz .LBB0_613
	v_div_scale_f32 v129, s[10:11], v133, v133, 1.0
	v_rcp_f32_e32 v131, v129
	s_add_u32 s16, s16, s74
	s_addc_u32 s17, s17, s75
	s_mov_b32 s4, 0xf800000
	v_fma_f32 v134, -v129, v131, 1.0
	v_fmac_f32_e32 v131, v134, v131
	v_div_scale_f32 v134, vcc, 1.0, v133, 1.0
	v_mul_f32_e32 v135, v134, v131
	v_fma_f32 v136, -v129, v135, v134
	v_fmac_f32_e32 v135, v136, v131
	v_fma_f32 v129, -v129, v135, v134
	v_div_fmas_f32 v129, v129, v131, v135
	v_div_fixup_f32 v134, v129, v133, 1.0
	v_div_scale_f32 v129, s[10:11], v132, v132, v236
	v_rcp_f32_e32 v131, v129
	s_mov_b64 s[10:11], 0x1fa00a00
	v_fma_f32 v133, -v129, v131, 1.0
	v_fmac_f32_e32 v131, v133, v131
	v_div_scale_f32 v133, vcc, v236, v132, v236
	v_mul_f32_e32 v135, v133, v131
	v_fma_f32 v136, -v129, v135, v133
	v_fmac_f32_e32 v135, v136, v131
	ds_read2st64_b32 v[208:209], v148 offset1:1
	ds_read2st64_b32 v[210:211], v148 offset0:2 offset1:3
	ds_read2st64_b32 v[204:205], v148 offset0:4 offset1:5
	ds_read2st64_b32 v[206:207], v148 offset0:6 offset1:7
	s_waitcnt vmcnt(0)
	ds_read2st64_b32 v[190:191], v148 offset0:8 offset1:9
	ds_read2st64_b32 v[202:203], v148 offset0:10 offset1:11
	ds_read2st64_b32 v[186:187], v148 offset0:12 offset1:13
	ds_read2st64_b32 v[188:189], v148 offset0:14 offset1:15
	ds_read2st64_b32 v[182:183], v148 offset0:16 offset1:17
	ds_read2st64_b32 v[184:185], v148 offset0:18 offset1:19
	ds_read2st64_b32 v[178:179], v148 offset0:20 offset1:21
	ds_read2st64_b32 v[180:181], v148 offset0:22 offset1:23
	ds_read2st64_b32 v[174:175], v148 offset0:24 offset1:25
	ds_read2st64_b32 v[176:177], v148 offset0:26 offset1:27
	ds_read2st64_b32 v[170:171], v148 offset0:28 offset1:29
	ds_read2st64_b32 v[172:173], v148 offset0:30 offset1:31
	ds_read2st64_b32 v[164:165], v148 offset0:32 offset1:33
	ds_read2st64_b32 v[166:167], v148 offset0:34 offset1:35
	ds_read2st64_b32 v[160:161], v148 offset0:36 offset1:37
	ds_read2st64_b32 v[162:163], v148 offset0:38 offset1:39
	ds_read2st64_b32 v[156:157], v148 offset0:40 offset1:41
	ds_read2st64_b32 v[158:159], v148 offset0:42 offset1:43
	ds_read2st64_b32 v[152:153], v148 offset0:44 offset1:45
	ds_read2st64_b32 v[154:155], v148 offset0:46 offset1:47
	ds_read2st64_b32 v[146:147], v148 offset0:48 offset1:49
	ds_read2st64_b32 v[150:151], v148 offset0:50 offset1:51
	ds_read2st64_b32 v[140:141], v148 offset0:52 offset1:53
	ds_read2st64_b32 v[142:143], v148 offset0:54 offset1:55
	ds_read2st64_b32 v[138:139], v148 offset0:56 offset1:57
	ds_read2st64_b32 v[136:137], v148 offset0:58 offset1:59
	v_fma_f32 v129, -v129, v135, v133
	v_div_fmas_f32 v129, v129, v131, v135
	v_div_fixup_f32 v132, v129, v132, v236
	s_waitcnt lgkmcnt(0)
	v_pk_mul_f32 v[136:137], v[130:131], v[136:137] op_sel_hi:[0,1]
	v_pk_fma_f32 v[26:27], v[26:27], v[128:129], v[136:137] op_sel_hi:[1,0,1]
	s_nop 0
	v_pk_mul_f32 v[26:27], v[132:133], v[26:27] op_sel_hi:[0,1]
	v_pk_fma_f32 v[26:27], v[10:11], v[134:135], v[26:27] op_sel_hi:[1,0,1] neg_lo:[0,0,1] neg_hi:[0,0,1]
	ds_read2st64_b32 v[10:11], v148 offset0:60 offset1:61
	v_pk_mul_f32 v[136:137], v[26:27], v[26:27]
	s_waitcnt lgkmcnt(0)
	v_pk_mul_f32 v[10:11], v[130:131], v[10:11] op_sel_hi:[0,1]
	v_pk_fma_f32 v[10:11], v[28:29], v[128:129], v[10:11] op_sel_hi:[1,0,1]
	s_nop 0
	v_pk_mul_f32 v[10:11], v[132:133], v[10:11] op_sel_hi:[0,1]
	v_pk_fma_f32 v[28:29], v[12:13], v[134:135], v[10:11] op_sel_hi:[1,0,1] neg_lo:[0,0,1] neg_hi:[0,0,1]
	ds_read2st64_b32 v[10:11], v148 offset0:62 offset1:63
	v_lshlrev_b32_e32 v12, 3, v239
	v_mov_b32_e32 v13, v193
	v_pk_mul_f32 v[144:145], v[28:29], v[28:29]
	s_waitcnt lgkmcnt(0)
	v_pk_mul_f32 v[10:11], v[130:131], v[10:11] op_sel_hi:[0,1]
	v_pk_fma_f32 v[10:11], v[30:31], v[128:129], v[10:11] op_sel_hi:[1,0,1]
	s_nop 0
	v_pk_mul_f32 v[10:11], v[132:133], v[10:11] op_sel_hi:[0,1]
	v_pk_fma_f32 v[30:31], v[14:15], v[134:135], v[10:11] op_sel_hi:[1,0,1] neg_lo:[0,0,1] neg_hi:[0,0,1]
	v_lshlrev_b64 v[10:11], 12, v[200:201]
	v_pk_mul_f32 v[200:201], v[130:131], v[210:211] op_sel_hi:[0,1]
	v_pk_fma_f32 v[98:99], v[98:99], v[128:129], v[200:201] op_sel_hi:[1,0,1]
	v_lshl_add_u64 v[10:11], s[12:13], 0, v[10:11]
	v_pk_mul_f32 v[98:99], v[132:133], v[98:99] op_sel_hi:[0,1]
	v_pk_fma_f32 v[98:99], v[114:115], v[134:135], v[98:99] op_sel_hi:[1,0,1] neg_lo:[0,0,1] neg_hi:[0,0,1]
	v_pk_mul_f32 v[114:115], v[130:131], v[208:209] op_sel_hi:[0,1]
	v_pk_fma_f32 v[96:97], v[96:97], v[128:129], v[114:115] op_sel_hi:[1,0,1]
	v_pk_mul_f32 v[200:201], v[98:99], v[98:99]
	v_pk_mul_f32 v[96:97], v[132:133], v[96:97] op_sel_hi:[0,1]
	v_pk_fma_f32 v[112:113], v[112:113], v[134:135], v[96:97] op_sel_hi:[1,0,1] neg_lo:[0,0,1] neg_hi:[0,0,1]
	v_pk_mul_f32 v[96:97], v[130:131], v[206:207] op_sel_hi:[0,1]
	v_pk_fma_f32 v[96:97], v[102:103], v[128:129], v[96:97] op_sel_hi:[1,0,1]
	v_pk_mul_f32 v[102:103], v[130:131], v[204:205] op_sel_hi:[0,1]
	v_pk_fma_f32 v[100:101], v[100:101], v[128:129], v[102:103] op_sel_hi:[1,0,1]
	v_pk_mul_f32 v[208:209], v[112:113], v[112:113]
	v_pk_mul_f32 v[100:101], v[132:133], v[100:101] op_sel_hi:[0,1]
	v_pk_fma_f32 v[114:115], v[116:117], v[134:135], v[100:101] op_sel_hi:[1,0,1] neg_lo:[0,0,1] neg_hi:[0,0,1]
	v_pk_mul_f32 v[100:101], v[130:131], v[202:203] op_sel_hi:[0,1]
	v_pk_fma_f32 v[100:101], v[106:107], v[128:129], v[100:101] op_sel_hi:[1,0,1]
	v_pk_mul_f32 v[106:107], v[130:131], v[186:187] op_sel_hi:[0,1]
	v_pk_fma_f32 v[106:107], v[108:109], v[128:129], v[106:107] op_sel_hi:[1,0,1]
	v_pk_mul_f32 v[96:97], v[132:133], v[96:97] op_sel_hi:[0,1]
	v_pk_mul_f32 v[106:107], v[132:133], v[106:107] op_sel_hi:[0,1]
	v_pk_fma_f32 v[108:109], v[124:125], v[134:135], v[106:107] op_sel_hi:[1,0,1] neg_lo:[0,0,1] neg_hi:[0,0,1]
	v_pk_mul_f32 v[106:107], v[130:131], v[184:185] op_sel_hi:[0,1]
	v_pk_fma_f32 v[82:83], v[82:83], v[128:129], v[106:107] op_sel_hi:[1,0,1]
	v_pk_mul_f32 v[116:117], v[114:115], v[114:115]
	v_pk_mul_f32 v[82:83], v[132:133], v[82:83] op_sel_hi:[0,1]
	v_pk_fma_f32 v[82:83], v[66:67], v[134:135], v[82:83] op_sel_hi:[1,0,1] neg_lo:[0,0,1] neg_hi:[0,0,1]
	v_pk_mul_f32 v[66:67], v[130:131], v[182:183] op_sel_hi:[0,1]
	v_pk_fma_f32 v[66:67], v[80:81], v[128:129], v[66:67] op_sel_hi:[1,0,1]
	v_pk_mul_f32 v[102:103], v[130:131], v[190:191] op_sel_hi:[0,1]
	v_pk_mul_f32 v[66:67], v[132:133], v[66:67] op_sel_hi:[0,1]
	v_pk_fma_f32 v[106:107], v[64:65], v[134:135], v[66:67] op_sel_hi:[1,0,1] neg_lo:[0,0,1] neg_hi:[0,0,1]
	v_pk_mul_f32 v[64:65], v[130:131], v[180:181] op_sel_hi:[0,1]
	v_pk_fma_f32 v[64:65], v[86:87], v[128:129], v[64:65] op_sel_hi:[1,0,1]
	v_pk_fma_f32 v[96:97], v[118:119], v[134:135], v[96:97] op_sel_hi:[1,0,1] neg_lo:[0,0,1] neg_hi:[0,0,1]
	v_pk_mul_f32 v[64:65], v[132:133], v[64:65] op_sel_hi:[0,1]
	v_pk_fma_f32 v[70:71], v[70:71], v[134:135], v[64:65] op_sel_hi:[1,0,1] neg_lo:[0,0,1] neg_hi:[0,0,1]
	v_pk_mul_f32 v[64:65], v[130:131], v[178:179] op_sel_hi:[0,1]
	v_pk_fma_f32 v[64:65], v[84:85], v[128:129], v[64:65] op_sel_hi:[1,0,1]
	v_pk_fma_f32 v[102:103], v[104:105], v[128:129], v[102:103] op_sel_hi:[1,0,1]
	v_pk_mul_f32 v[64:65], v[132:133], v[64:65] op_sel_hi:[0,1]
	v_pk_fma_f32 v[80:81], v[68:69], v[134:135], v[64:65] op_sel_hi:[1,0,1] neg_lo:[0,0,1] neg_hi:[0,0,1]
	v_pk_mul_f32 v[64:65], v[130:131], v[176:177] op_sel_hi:[0,1]
	v_pk_fma_f32 v[64:65], v[90:91], v[128:129], v[64:65] op_sel_hi:[1,0,1]
	v_pk_mul_f32 v[68:69], v[130:131], v[170:171] op_sel_hi:[0,1]
	v_pk_mul_f32 v[64:65], v[132:133], v[64:65] op_sel_hi:[0,1]
	v_pk_fma_f32 v[66:67], v[74:75], v[134:135], v[64:65] op_sel_hi:[1,0,1] neg_lo:[0,0,1] neg_hi:[0,0,1]
	v_pk_mul_f32 v[64:65], v[130:131], v[174:175] op_sel_hi:[0,1]
	v_pk_fma_f32 v[64:65], v[88:89], v[128:129], v[64:65] op_sel_hi:[1,0,1]
	v_pk_fma_f32 v[68:69], v[92:93], v[128:129], v[68:69] op_sel_hi:[1,0,1]
	v_pk_mul_f32 v[64:65], v[132:133], v[64:65] op_sel_hi:[0,1]
	v_pk_mul_f32 v[68:69], v[132:133], v[68:69] op_sel_hi:[0,1]
	v_pk_fma_f32 v[74:75], v[72:73], v[134:135], v[64:65] op_sel_hi:[1,0,1] neg_lo:[0,0,1] neg_hi:[0,0,1]
	v_pk_fma_f32 v[72:73], v[76:77], v[134:135], v[68:69] op_sel_hi:[1,0,1] neg_lo:[0,0,1] neg_hi:[0,0,1]
	v_pk_mul_f32 v[68:69], v[130:131], v[166:167] op_sel_hi:[0,1]
	v_pk_fma_f32 v[50:51], v[50:51], v[128:129], v[68:69] op_sel_hi:[1,0,1]
	v_pk_mul_f32 v[118:119], v[96:97], v[96:97]
	v_pk_mul_f32 v[50:51], v[132:133], v[50:51] op_sel_hi:[0,1]
	v_pk_fma_f32 v[50:51], v[34:35], v[134:135], v[50:51] op_sel_hi:[1,0,1] neg_lo:[0,0,1] neg_hi:[0,0,1]
	v_pk_mul_f32 v[34:35], v[130:131], v[164:165] op_sel_hi:[0,1]
	v_pk_fma_f32 v[34:35], v[48:49], v[128:129], v[34:35] op_sel_hi:[1,0,1]
	v_pk_mul_f32 v[102:103], v[132:133], v[102:103] op_sel_hi:[0,1]
	v_pk_mul_f32 v[34:35], v[132:133], v[34:35] op_sel_hi:[0,1]
	v_pk_fma_f32 v[68:69], v[32:33], v[134:135], v[34:35] op_sel_hi:[1,0,1] neg_lo:[0,0,1] neg_hi:[0,0,1]
	v_pk_mul_f32 v[32:33], v[130:131], v[162:163] op_sel_hi:[0,1]
	v_pk_fma_f32 v[32:33], v[54:55], v[128:129], v[32:33] op_sel_hi:[1,0,1]
	v_pk_fma_f32 v[104:105], v[120:121], v[134:135], v[102:103] op_sel_hi:[1,0,1] neg_lo:[0,0,1] neg_hi:[0,0,1]
	v_pk_mul_f32 v[32:33], v[132:133], v[32:33] op_sel_hi:[0,1]
	v_pk_fma_f32 v[38:39], v[38:39], v[134:135], v[32:33] op_sel_hi:[1,0,1] neg_lo:[0,0,1] neg_hi:[0,0,1]
	v_pk_mul_f32 v[32:33], v[130:131], v[160:161] op_sel_hi:[0,1]
	v_pk_fma_f32 v[32:33], v[52:53], v[128:129], v[32:33] op_sel_hi:[1,0,1]
	v_pk_mul_f32 v[100:101], v[132:133], v[100:101] op_sel_hi:[0,1]
	v_pk_mul_f32 v[32:33], v[132:133], v[32:33] op_sel_hi:[0,1]
	v_pk_fma_f32 v[48:49], v[36:37], v[134:135], v[32:33] op_sel_hi:[1,0,1] neg_lo:[0,0,1] neg_hi:[0,0,1]
	v_pk_mul_f32 v[32:33], v[130:131], v[158:159] op_sel_hi:[0,1]
	v_pk_fma_f32 v[32:33], v[58:59], v[128:129], v[32:33] op_sel_hi:[1,0,1]
	v_pk_mul_f32 v[58:59], v[130:131], v[150:151] op_sel_hi:[0,1]
	v_pk_fma_f32 v[18:19], v[18:19], v[128:129], v[58:59] op_sel_hi:[1,0,1]
	v_pk_mul_f32 v[120:121], v[104:105], v[104:105]
	v_pk_mul_f32 v[18:19], v[132:133], v[18:19] op_sel_hi:[0,1]
	v_pk_fma_f32 v[18:19], v[2:3], v[134:135], v[18:19] op_sel_hi:[1,0,1] neg_lo:[0,0,1] neg_hi:[0,0,1]
	v_pk_mul_f32 v[2:3], v[130:131], v[146:147] op_sel_hi:[0,1]
	v_pk_fma_f32 v[2:3], v[16:17], v[128:129], v[2:3] op_sel_hi:[1,0,1]
	v_pk_fma_f32 v[100:101], v[122:123], v[134:135], v[100:101] op_sel_hi:[1,0,1] neg_lo:[0,0,1] neg_hi:[0,0,1]
	v_pk_mul_f32 v[2:3], v[132:133], v[2:3] op_sel_hi:[0,1]
	v_pk_fma_f32 v[16:17], v[0:1], v[134:135], v[2:3] op_sel_hi:[1,0,1] neg_lo:[0,0,1] neg_hi:[0,0,1]
	v_pk_mul_f32 v[0:1], v[130:131], v[142:143] op_sel_hi:[0,1]
	v_pk_fma_f32 v[0:1], v[22:23], v[128:129], v[0:1] op_sel_hi:[1,0,1]
	v_add_f32_e32 v22, v208, v209
	v_add_f32_e32 v22, v22, v200
	v_add_f32_e32 v22, v22, v201
	v_add_f32_e32 v22, v22, v116
	v_add_f32_e32 v22, v22, v117
	v_add_f32_e32 v22, v22, v118
	v_add_f32_e32 v22, v22, v119
	v_add_f32_e32 v22, v22, v120
	v_pk_mul_f32 v[122:123], v[100:101], v[100:101]
	v_pk_mul_f32 v[102:103], v[130:131], v[188:189] op_sel_hi:[0,1]
	v_add_f32_e32 v22, v22, v121
	v_pk_fma_f32 v[102:103], v[110:111], v[128:129], v[102:103] op_sel_hi:[1,0,1]
	v_add_f32_e32 v22, v22, v122
	v_pk_mul_f32 v[102:103], v[132:133], v[102:103] op_sel_hi:[0,1]
	v_pk_mul_f32 v[124:125], v[108:109], v[108:109]
	v_add_f32_e32 v22, v22, v123
	v_pk_fma_f32 v[102:103], v[126:127], v[134:135], v[102:103] op_sel_hi:[1,0,1] neg_lo:[0,0,1] neg_hi:[0,0,1]
	v_add_f32_e32 v22, v22, v124
	v_pk_mul_f32 v[110:111], v[102:103], v[102:103]
	v_add_f32_e32 v22, v22, v125
	v_add_f32_e32 v22, v22, v110
	v_pk_mul_f32 v[182:183], v[106:107], v[106:107]
	v_add_f32_e32 v22, v22, v111
	v_add_f32_e32 v22, v22, v182
	v_pk_mul_f32 v[126:127], v[82:83], v[82:83]
	v_add_f32_e32 v22, v22, v183
	v_add_f32_e32 v22, v22, v126
	v_lshl_add_u64 v[10:11], s[14:15], 1, v[10:11]
	v_pk_mul_f32 v[84:85], v[80:81], v[80:81]
	v_add_f32_e32 v22, v22, v127
	v_lshl_add_u64 v[148:149], v[10:11], 0, v[12:13]
	global_load_dwordx4 v[10:13], v192, s[16:17]
	global_load_dwordx4 v[116:119], v192, s[16:17] offset:32
	global_load_dwordx4 v[120:123], v192, s[16:17] offset:64
	global_load_dwordx4 v[124:127], v192, s[16:17] offset:96
	global_load_dwordx4 v[160:163], v192, s[16:17] offset:128
	global_load_dwordx4 v[164:167], v192, s[16:17] offset:160
	global_load_dwordx4 v[176:179], v192, s[16:17] offset:192
	global_load_dwordx4 v[180:183], v192, s[16:17] offset:224
	global_load_dwordx4 v[184:187], v192, s[16:17] offset:256
	global_load_dwordx4 v[188:191], v192, s[16:17] offset:288
	global_load_dwordx4 v[200:203], v192, s[16:17] offset:320
	global_load_dwordx4 v[204:207], v192, s[16:17] offset:352
	global_load_dwordx4 v[208:211], v192, s[16:17] offset:384
	global_load_dwordx4 v[240:243], v192, s[16:17] offset:416
	global_load_dwordx4 v[244:247], v192, s[16:17] offset:448
	global_load_dwordx4 v[248:251], v192, s[16:17] offset:480
	v_add_f32_e32 v22, v22, v84
	v_pk_mul_f32 v[86:87], v[70:71], v[70:71]
	v_add_f32_e32 v22, v22, v85
	v_add_f32_e32 v22, v22, v86
	v_pk_mul_f32 v[88:89], v[74:75], v[74:75]
	v_add_f32_e32 v22, v22, v87
	v_add_f32_e32 v22, v22, v88
	v_pk_mul_f32 v[90:91], v[66:67], v[66:67]
	v_pk_mul_f32 v[64:65], v[130:131], v[172:173] op_sel_hi:[0,1]
	v_add_f32_e32 v22, v22, v89
	v_pk_fma_f32 v[64:65], v[94:95], v[128:129], v[64:65] op_sel_hi:[1,0,1]
	v_add_f32_e32 v22, v22, v90
	v_pk_mul_f32 v[64:65], v[132:133], v[64:65] op_sel_hi:[0,1]
	v_pk_mul_f32 v[76:77], v[72:73], v[72:73]
	v_add_f32_e32 v22, v22, v91
	v_pk_fma_f32 v[64:65], v[78:79], v[134:135], v[64:65] op_sel_hi:[1,0,1] neg_lo:[0,0,1] neg_hi:[0,0,1]
	v_add_f32_e32 v22, v22, v76
	v_pk_mul_f32 v[78:79], v[64:65], v[64:65]
	v_add_f32_e32 v22, v22, v77
	v_add_f32_e32 v22, v22, v78
	v_pk_mul_f32 v[94:95], v[68:69], v[68:69]
	v_add_f32_e32 v22, v22, v79
	v_add_f32_e32 v22, v22, v94
	v_pk_mul_f32 v[92:93], v[50:51], v[50:51]
	v_add_f32_e32 v22, v22, v95
	v_pk_mul_f32 v[32:33], v[132:133], v[32:33] op_sel_hi:[0,1]
	v_add_f32_e32 v22, v22, v92
	v_pk_mul_f32 v[52:53], v[48:49], v[48:49]
	v_pk_fma_f32 v[34:35], v[42:43], v[134:135], v[32:33] op_sel_hi:[1,0,1] neg_lo:[0,0,1] neg_hi:[0,0,1]
	v_pk_mul_f32 v[32:33], v[130:131], v[156:157] op_sel_hi:[0,1]
	v_add_f32_e32 v22, v22, v93
	v_pk_fma_f32 v[32:33], v[56:57], v[128:129], v[32:33] op_sel_hi:[1,0,1]
	v_add_f32_e32 v22, v22, v52
	v_pk_mul_f32 v[54:55], v[38:39], v[38:39]
	v_pk_mul_f32 v[32:33], v[132:133], v[32:33] op_sel_hi:[0,1]
	v_add_f32_e32 v22, v22, v53
	v_pk_fma_f32 v[40:41], v[40:41], v[134:135], v[32:33] op_sel_hi:[1,0,1] neg_lo:[0,0,1] neg_hi:[0,0,1]
	v_add_f32_e32 v22, v22, v54
	v_pk_mul_f32 v[56:57], v[40:41], v[40:41]
	v_pk_mul_f32 v[36:37], v[130:131], v[152:153] op_sel_hi:[0,1]
	v_add_f32_e32 v22, v22, v55
	v_pk_fma_f32 v[36:37], v[60:61], v[128:129], v[36:37] op_sel_hi:[1,0,1]
	v_add_f32_e32 v22, v22, v56
	v_pk_mul_f32 v[42:43], v[34:35], v[34:35]
	v_pk_mul_f32 v[32:33], v[130:131], v[154:155] op_sel_hi:[0,1]
	v_pk_mul_f32 v[36:37], v[132:133], v[36:37] op_sel_hi:[0,1]
	v_add_f32_e32 v22, v22, v57
	v_pk_fma_f32 v[32:33], v[62:63], v[128:129], v[32:33] op_sel_hi:[1,0,1]
	v_pk_fma_f32 v[36:37], v[44:45], v[134:135], v[36:37] op_sel_hi:[1,0,1] neg_lo:[0,0,1] neg_hi:[0,0,1]
	v_add_f32_e32 v22, v22, v42
	v_pk_mul_f32 v[32:33], v[132:133], v[32:33] op_sel_hi:[0,1]
	v_pk_mul_f32 v[44:45], v[36:37], v[36:37]
	v_add_f32_e32 v22, v22, v43
	v_pk_fma_f32 v[32:33], v[46:47], v[134:135], v[32:33] op_sel_hi:[1,0,1] neg_lo:[0,0,1] neg_hi:[0,0,1]
	v_add_f32_e32 v22, v22, v44
	v_pk_mul_f32 v[46:47], v[32:33], v[32:33]
	v_add_f32_e32 v22, v22, v45
	v_add_f32_e32 v22, v22, v46
	v_pk_mul_f32 v[60:61], v[16:17], v[16:17]
	v_pk_mul_f32 v[2:3], v[130:131], v[140:141] op_sel_hi:[0,1]
	v_add_f32_e32 v22, v22, v47
	v_pk_fma_f32 v[2:3], v[20:21], v[128:129], v[2:3] op_sel_hi:[1,0,1]
	v_add_f32_e32 v22, v22, v60
	v_pk_mul_f32 v[58:59], v[18:19], v[18:19]
	v_pk_mul_f32 v[2:3], v[132:133], v[2:3] op_sel_hi:[0,1]
	v_add_f32_e32 v22, v22, v61
	v_pk_fma_f32 v[4:5], v[4:5], v[134:135], v[2:3] op_sel_hi:[1,0,1] neg_lo:[0,0,1] neg_hi:[0,0,1]
	v_add_f32_e32 v22, v22, v58
	v_pk_mul_f32 v[0:1], v[132:133], v[0:1] op_sel_hi:[0,1]
	v_pk_mul_f32 v[20:21], v[4:5], v[4:5]
	v_pk_mul_f32 v[2:3], v[130:131], v[138:139] op_sel_hi:[0,1]
	v_add_f32_e32 v22, v22, v59
	v_pk_fma_f32 v[0:1], v[6:7], v[134:135], v[0:1] op_sel_hi:[1,0,1] neg_lo:[0,0,1] neg_hi:[0,0,1]
	v_pk_fma_f32 v[2:3], v[24:25], v[128:129], v[2:3] op_sel_hi:[1,0,1]
	v_add_f32_e32 v20, v22, v20
	v_pk_mul_f32 v[6:7], v[0:1], v[0:1]
	v_pk_mul_f32 v[2:3], v[132:133], v[2:3] op_sel_hi:[0,1]
	v_add_f32_e32 v20, v20, v21
	v_pk_fma_f32 v[2:3], v[8:9], v[134:135], v[2:3] op_sel_hi:[1,0,1] neg_lo:[0,0,1] neg_hi:[0,0,1]
	v_add_f32_e32 v6, v20, v6
	v_pk_mul_f32 v[8:9], v[2:3], v[2:3]
	v_add_f32_e32 v6, v6, v7
	v_add_f32_e32 v6, v6, v8
	v_add_f32_e32 v6, v6, v9
	v_add_f32_e32 v6, v6, v136
	v_add_f32_e32 v6, v6, v137
	v_add_f32_e32 v6, v6, v144
	v_pk_mul_f32 v[168:169], v[30:31], v[30:31]
	v_add_f32_e32 v6, v6, v145
	v_add_f32_e32 v6, v6, v168
	v_add_f32_e32 v6, v6, v169
	ds_bpermute_b32 v7, v235, v6
	v_lshl_add_u64 v[14:15], v[148:149], 0, s[10:11]
	s_waitcnt lgkmcnt(0)
	v_add_f32_e32 v6, v6, v7
	v_fmamk_f32 v6, v6, 0x3c000000, v219
	v_cmp_gt_f32_e32 vcc, s4, v6
	v_mul_f32_e32 v7, 0x4f800000, v6
	s_mov_b32 s4, 0x1fa00000
	v_cndmask_b32_e32 v6, v6, v7, vcc
	v_sqrt_f32_e32 v7, v6
	s_nop 0
	v_add_u32_e32 v8, -1, v7
	v_fma_f32 v9, -v8, v7, v6
	v_cmp_ge_f32_e64 s[10:11], 0, v9
	v_add_u32_e32 v9, 1, v7
	s_nop 0
	v_cndmask_b32_e64 v8, v7, v8, s[10:11]
	v_fma_f32 v7, -v9, v7, v6
	v_cmp_lt_f32_e64 s[10:11], 0, v7
	s_nop 1
	v_cndmask_b32_e64 v7, v8, v9, s[10:11]
	v_mul_f32_e32 v8, 0x37800000, v7
	v_cndmask_b32_e32 v7, v7, v8, vcc
	v_cmp_class_f32_e32 vcc, v6, v220
	s_nop 1
	v_cndmask_b32_e32 v6, v7, v6, vcc
	v_div_scale_f32 v7, s[10:11], v6, v6, v238
	v_rcp_f32_e32 v8, v7
	s_nop 0
	v_fma_f32 v9, -v7, v8, 1.0
	v_fmac_f32_e32 v8, v9, v8
	v_div_scale_f32 v9, vcc, v238, v6, v238
	v_mul_f32_e32 v20, v9, v8
	v_fma_f32 v21, -v7, v20, v9
	v_fmac_f32_e32 v20, v21, v8
	v_fma_f32 v7, -v7, v20, v9
	v_div_fmas_f32 v7, v7, v8, v20
	v_div_fixup_f32 v6, v7, v6, v238
	v_and_b32_e32 v20, 32, v223
	v_lshrrev_b32_e32 v20, 2, v20
	v_mov_b32_e32 v21, 0
	v_lshl_add_u64 v[14:15], v[20:21], 0, v[14:15]
	v_pk_mul_f32 v[8:9], v[112:113], v[6:7] op_sel_hi:[1,0]
	v_pk_mul_f32 v[4:5], v[4:5], v[6:7] op_sel_hi:[1,0]
	s_waitcnt vmcnt(0)
	v_pk_mul_f32 v[8:9], v[10:11], v[8:9]
	v_pk_mul_f32 v[10:11], v[98:99], v[6:7] op_sel_hi:[1,0]
	v_cvt_pk_bf16_f32 v52, v8, v9
	v_pk_mul_f32 v[10:11], v[12:13], v[10:11]
	v_pk_mul_f32 v[12:13], v[114:115], v[6:7] op_sel_hi:[1,0]
	v_cvt_pk_bf16_f32 v53, v10, v11
	v_add_co_u32_e32 v10, vcc, s4, v148
	v_pk_mul_f32 v[0:1], v[0:1], v[6:7] op_sel_hi:[1,0]
	s_nop 0
	v_addc_co_u32_e32 v11, vcc, 0, v149, vcc
	v_mov_b64_e32 v[8:9], v[116:117]
	v_mov_b64_e32 v[10:11], v[118:119]
	v_pk_mul_f32 v[8:9], v[8:9], v[12:13]
	v_pk_mul_f32 v[12:13], v[96:97], v[6:7] op_sel_hi:[1,0]
	v_cvt_pk_bf16_f32 v54, v8, v9
	v_pk_mul_f32 v[10:11], v[10:11], v[12:13]
	v_pk_mul_f32 v[12:13], v[104:105], v[6:7] op_sel_hi:[1,0]
	v_cvt_pk_bf16_f32 v55, v10, v11
	s_nop 1
	v_permlane32_swap_b32_e32 v52, v54
	v_permlane32_swap_b32_e32 v53, v55
	global_store_dwordx4 v[14:15], v[52:55], off
	v_mov_b64_e32 v[8:9], v[120:121]
	v_mov_b64_e32 v[10:11], v[122:123]
	v_pk_mul_f32 v[8:9], v[8:9], v[12:13]
	v_pk_mul_f32 v[12:13], v[100:101], v[6:7] op_sel_hi:[1,0]
	v_cvt_pk_bf16_f32 v56, v8, v9
	v_pk_mul_f32 v[10:11], v[10:11], v[12:13]
	v_pk_mul_f32 v[12:13], v[108:109], v[6:7] op_sel_hi:[1,0]
	v_cvt_pk_bf16_f32 v57, v10, v11
	v_mov_b64_e32 v[8:9], v[124:125]
	v_mov_b64_e32 v[10:11], v[126:127]
	v_pk_mul_f32 v[8:9], v[8:9], v[12:13]
	v_pk_mul_f32 v[12:13], v[102:103], v[6:7] op_sel_hi:[1,0]
	v_cvt_pk_bf16_f32 v58, v8, v9
	v_pk_mul_f32 v[10:11], v[10:11], v[12:13]
	v_pk_mul_f32 v[12:13], v[106:107], v[6:7] op_sel_hi:[1,0]
	v_cvt_pk_bf16_f32 v59, v10, v11
	s_nop 1
	v_permlane32_swap_b32_e32 v56, v58
	v_permlane32_swap_b32_e32 v57, v59
	global_store_dwordx4 v[14:15], v[56:59], off offset:32
	v_mov_b64_e32 v[8:9], v[160:161]
	v_mov_b64_e32 v[10:11], v[162:163]
	v_pk_mul_f32 v[8:9], v[8:9], v[12:13]
	v_pk_mul_f32 v[12:13], v[82:83], v[6:7] op_sel_hi:[1,0]
	v_cvt_pk_bf16_f32 v60, v8, v9
	v_pk_mul_f32 v[10:11], v[10:11], v[12:13]
	v_pk_mul_f32 v[12:13], v[80:81], v[6:7] op_sel_hi:[1,0]
	v_cvt_pk_bf16_f32 v61, v10, v11
	v_mov_b64_e32 v[8:9], v[164:165]
	v_mov_b64_e32 v[10:11], v[166:167]
	v_pk_mul_f32 v[8:9], v[8:9], v[12:13]
	v_pk_mul_f32 v[12:13], v[70:71], v[6:7] op_sel_hi:[1,0]
	v_cvt_pk_bf16_f32 v62, v8, v9
	v_pk_mul_f32 v[10:11], v[10:11], v[12:13]
	v_pk_mul_f32 v[12:13], v[74:75], v[6:7] op_sel_hi:[1,0]
	v_cvt_pk_bf16_f32 v63, v10, v11
	s_nop 1
	v_permlane32_swap_b32_e32 v60, v62
	v_permlane32_swap_b32_e32 v61, v63
	global_store_dwordx4 v[14:15], v[60:63], off offset:64
	v_mov_b64_e32 v[8:9], v[176:177]
	v_mov_b64_e32 v[10:11], v[178:179]
	v_pk_mul_f32 v[8:9], v[12:13], v[8:9]
	v_pk_mul_f32 v[12:13], v[66:67], v[6:7] op_sel_hi:[1,0]
	v_cvt_pk_bf16_f32 v84, v8, v9
	v_pk_mul_f32 v[10:11], v[12:13], v[10:11]
	v_pk_mul_f32 v[12:13], v[72:73], v[6:7] op_sel_hi:[1,0]
	v_cvt_pk_bf16_f32 v85, v10, v11
	v_mov_b64_e32 v[8:9], v[180:181]
	v_mov_b64_e32 v[10:11], v[182:183]
	v_pk_mul_f32 v[8:9], v[12:13], v[8:9]
	v_pk_mul_f32 v[12:13], v[64:65], v[6:7] op_sel_hi:[1,0]
	v_cvt_pk_bf16_f32 v86, v8, v9
	v_pk_mul_f32 v[10:11], v[12:13], v[10:11]
	v_pk_mul_f32 v[12:13], v[68:69], v[6:7] op_sel_hi:[1,0]
	v_cvt_pk_bf16_f32 v87, v10, v11
	s_nop 1
	v_permlane32_swap_b32_e32 v84, v86
	v_permlane32_swap_b32_e32 v85, v87
	global_store_dwordx4 v[14:15], v[84:87], off offset:96
	v_mov_b64_e32 v[8:9], v[184:185]
	v_mov_b64_e32 v[10:11], v[186:187]
	v_pk_mul_f32 v[8:9], v[12:13], v[8:9]
	v_pk_mul_f32 v[12:13], v[50:51], v[6:7] op_sel_hi:[1,0]
	v_cvt_pk_bf16_f32 v52, v8, v9
	v_pk_mul_f32 v[10:11], v[12:13], v[10:11]
	v_pk_mul_f32 v[12:13], v[48:49], v[6:7] op_sel_hi:[1,0]
	v_cvt_pk_bf16_f32 v53, v10, v11
	v_mov_b64_e32 v[8:9], v[188:189]
	v_mov_b64_e32 v[10:11], v[190:191]
	v_pk_mul_f32 v[8:9], v[12:13], v[8:9]
	v_pk_mul_f32 v[12:13], v[38:39], v[6:7] op_sel_hi:[1,0]
	v_cvt_pk_bf16_f32 v54, v8, v9
	v_pk_mul_f32 v[10:11], v[12:13], v[10:11]
	v_pk_mul_f32 v[12:13], v[40:41], v[6:7] op_sel_hi:[1,0]
	v_cvt_pk_bf16_f32 v55, v10, v11
	s_nop 1
	v_permlane32_swap_b32_e32 v52, v54
	v_permlane32_swap_b32_e32 v53, v55
	global_store_dwordx4 v[14:15], v[52:55], off offset:128
	v_mov_b64_e32 v[8:9], v[200:201]
	v_mov_b64_e32 v[10:11], v[202:203]
	v_pk_mul_f32 v[8:9], v[12:13], v[8:9]
	v_pk_mul_f32 v[12:13], v[34:35], v[6:7] op_sel_hi:[1,0]
	v_cvt_pk_bf16_f32 v56, v8, v9
	v_pk_mul_f32 v[10:11], v[12:13], v[10:11]
	v_pk_mul_f32 v[12:13], v[36:37], v[6:7] op_sel_hi:[1,0]
	v_cvt_pk_bf16_f32 v57, v10, v11
	v_mov_b64_e32 v[8:9], v[204:205]
	v_mov_b64_e32 v[10:11], v[206:207]
	v_pk_mul_f32 v[8:9], v[12:13], v[8:9]
	v_pk_mul_f32 v[12:13], v[32:33], v[6:7] op_sel_hi:[1,0]
	v_cvt_pk_bf16_f32 v58, v8, v9
	v_pk_mul_f32 v[10:11], v[12:13], v[10:11]
	v_pk_mul_f32 v[12:13], v[16:17], v[6:7] op_sel_hi:[1,0]
	v_cvt_pk_bf16_f32 v59, v10, v11
	s_nop 1
	v_permlane32_swap_b32_e32 v56, v58
	v_permlane32_swap_b32_e32 v57, v59
	global_store_dwordx4 v[14:15], v[56:59], off offset:160
	v_mov_b64_e32 v[8:9], v[208:209]
	v_mov_b64_e32 v[10:11], v[210:211]
	v_pk_mul_f32 v[8:9], v[12:13], v[8:9]
	v_pk_mul_f32 v[12:13], v[18:19], v[6:7] op_sel_hi:[1,0]
	v_cvt_pk_bf16_f32 v60, v8, v9
	v_pk_mul_f32 v[10:11], v[12:13], v[10:11]
	s_nop 0
	v_cvt_pk_bf16_f32 v61, v10, v11
	v_mov_b64_e32 v[8:9], v[240:241]
	v_mov_b64_e32 v[10:11], v[242:243]
	v_pk_mul_f32 v[4:5], v[4:5], v[8:9]
	v_pk_mul_f32 v[0:1], v[0:1], v[10:11]
	v_cvt_pk_bf16_f32 v62, v4, v5
	v_cvt_pk_bf16_f32 v63, v0, v1
	s_nop 1
	v_permlane32_swap_b32_e32 v60, v62
	v_permlane32_swap_b32_e32 v61, v63
	global_store_dwordx4 v[14:15], v[60:63], off offset:192
	v_mov_b64_e32 v[8:9], v[244:245]
	v_mov_b64_e32 v[10:11], v[246:247]
	v_pk_mul_f32 v[0:1], v[2:3], v[6:7] op_sel_hi:[1,0]
	v_pk_mul_f32 v[2:3], v[26:27], v[6:7] op_sel_hi:[1,0]
	v_pk_mul_f32 v[4:5], v[28:29], v[6:7] op_sel_hi:[1,0]
	v_pk_mul_f32 v[0:1], v[0:1], v[8:9]
	v_pk_mul_f32 v[2:3], v[2:3], v[10:11]
	v_cvt_pk_bf16_f32 v84, v0, v1
	v_cvt_pk_bf16_f32 v85, v2, v3
	v_mov_b64_e32 v[0:1], v[248:249]
	v_mov_b64_e32 v[2:3], v[250:251]
	v_pk_mul_f32 v[0:1], v[4:5], v[0:1]
	v_pk_mul_f32 v[4:5], v[30:31], v[6:7] op_sel_hi:[1,0]
	v_cvt_pk_bf16_f32 v86, v0, v1
	v_pk_mul_f32 v[2:3], v[4:5], v[2:3]
	s_nop 0
	v_cvt_pk_bf16_f32 v87, v2, v3
	s_nop 1
	v_permlane32_swap_b32_e32 v84, v86
	v_permlane32_swap_b32_e32 v85, v87
	global_store_dwordx4 v[14:15], v[84:87], off offset:224
